# w_out epilogue: per-row vmcnt(0) waits of the bf16-residual path removed (rows are preloaded), f32 path waits moved behind its own loads
# speedup vs baseline: 1.0154x; 1.0154x over previous
; __device__ __forceinline__ void st16_wt(void* p, u32x4 v) { asm volatile("global_store_dwordx4 %0, %1, off sc1\n\ts_nop 1" :: "v"(p), "v"(v) : "memory"); }
; __device__ __forceinline__ void st16_wt(void* p, f32x4 v) { asm volatile("global_store_dwordx4 %0, %1, off sc1\n\ts_nop 1" :: "v"(p), "v"(v) : "memory"); }
; __device__ __forceinline__ void st4_wt(float* p, float v) { asm volatile("global_store_dword %0, %1, off sc1\n\ts_nop 1" :: "v"(p), "v"(v) : "memory"); }
; __device__ __forceinline__ u32x4 pack8(const f32x4& a, const f32x4& b) { u32x4 w; w.x = cvt_pk_bf16(a[0], a[1]); w.y = cvt_pk_bf16(a[2], a[3]); w.z = cvt_pk_bf16(b[0], b[1]); w.w = cvt_pk_bf16(b[2], b[3]); return w; }
; __device__ __forceinline__ float hsq4(const f32x4& v) { return (v[0] * v[0] + v[1] * v[1]) + (v[2] * v[2] + v[3] * v[3]); }
; __device__ __forceinline__ float red_fq(float s) { s += shfl_xor_(s, 16); s += shfl_xor_(s, 32); return s; }
; __device__ __forceinline__ f32x4 unpk_lo(unsigned a, unsigned b) { return (f32x4){__uint_as_float(a << 16), __uint_as_float(a & 0xffff0000u), __uint_as_float(b << 16), __uint_as_float(b & 0xffff0000u)}; }
;     __device__ __forceinline__ void operator()(const f32x4 (&acc)[2][2][4][2], const Unit& u, int wr, int wc, int fr, int fq) const {
;     ...
;             for (int m = 0; m < 4; ++m) { const int row = u.pm * BM + ai * HALF + wr * 64 + m * 16 + fr;
;                 float s = 0.f;
; #pragma unroll
;                 for (int bj = 0; bj < 2; ++bj) { const size_t o = (size_t)row * DM + u.pn * 256 + bj * HALF + cb;
;                     f32x4 a0, a1;
;                     if (xin_f32) { a0 = *(const f32x4*)(xin_f32 + o); a1 = *(const f32x4*)(xin_f32 + o + 4); }
;                     else { const u32x4 w = rw[m][bj]; a0 = unpk_lo(w.x, w.y); a1 = unpk_lo(w.z, w.w); }
;                     a0 = a0 + acc[ai][bj][m][0]; a1 = a1 + acc[ai][bj][m][1];
;                     if (WT) st16_wt(xb + o, pack8(a0, a1)); else *(u32x4*)(xb + o) = pack8(a0, a1); s += hsq4(a0) + hsq4(a1); }
;                 s = red_fq(s); if (fq == 0) { if (WT) st4_wt(rsx + (size_t)row * 16 + u.pn * 4 + wc, s); else rsx[(size_t)row * 16 + u.pn * 4 + wc] = s; }
;                 asm volatile("" ::: "memory"); } }
.LBB0_1531:
	v_lshlrev_b64 v[162:163], 10, v[180:181]
	v_lshl_add_u64 v[162:163], v[162:163], 0, v[182:183]
	v_lshl_add_u64 v[188:189], v[162:163], 0, s[54:55]
	s_and_b64 vcc, exec, s[6:7]
	v_lshl_add_u64 v[184:185], v[188:189], 2, s[24:25]
	s_cbranch_vccnz .LBB0_1606
	global_load_dwordx4 v[166:169], v[184:185], off offset:16
	global_load_dwordx4 v[162:165], v[184:185], off
	s_waitcnt vmcnt(0)
	s_cbranch_execnz .LBB0_1534

; __device__ __forceinline__ void st16_wt(void* p, u32x4 v) { asm volatile("global_store_dwordx4 %0, %1, off sc1\n\ts_nop 1" :: "v"(p), "v"(v) : "memory"); }
; __device__ __forceinline__ void st16_wt(void* p, f32x4 v) { asm volatile("global_store_dwordx4 %0, %1, off sc1\n\ts_nop 1" :: "v"(p), "v"(v) : "memory"); }
; __device__ __forceinline__ void st4_wt(float* p, float v) { asm volatile("global_store_dword %0, %1, off sc1\n\ts_nop 1" :: "v"(p), "v"(v) : "memory"); }
; __device__ __forceinline__ u32x4 pack8(const f32x4& a, const f32x4& b) { u32x4 w; w.x = cvt_pk_bf16(a[0], a[1]); w.y = cvt_pk_bf16(a[2], a[3]); w.z = cvt_pk_bf16(b[0], b[1]); w.w = cvt_pk_bf16(b[2], b[3]); return w; }
; __device__ __forceinline__ float hsq4(const f32x4& v) { return (v[0] * v[0] + v[1] * v[1]) + (v[2] * v[2] + v[3] * v[3]); }
; __device__ __forceinline__ float red_fq(float s) { s += shfl_xor_(s, 16); s += shfl_xor_(s, 32); return s; }
; __device__ __forceinline__ f32x4 unpk_lo(unsigned a, unsigned b) { return (f32x4){__uint_as_float(a << 16), __uint_as_float(a & 0xffff0000u), __uint_as_float(b << 16), __uint_as_float(b & 0xffff0000u)}; }
;     __device__ __forceinline__ void operator()(const f32x4 (&acc)[2][2][4][2], const Unit& u, int wr, int wc, int fr, int fq) const {
;     ...
;             for (int m = 0; m < 4; ++m) { const int row = u.pm * BM + ai * HALF + wr * 64 + m * 16 + fr;
;                 float s = 0.f;
; #pragma unroll
;                 for (int bj = 0; bj < 2; ++bj) { const size_t o = (size_t)row * DM + u.pn * 256 + bj * HALF + cb;
;                     f32x4 a0, a1;
;                     if (xin_f32) { a0 = *(const f32x4*)(xin_f32 + o); a1 = *(const f32x4*)(xin_f32 + o + 4); }
;                     else { const u32x4 w = rw[m][bj]; a0 = unpk_lo(w.x, w.y); a1 = unpk_lo(w.z, w.w); }
;                     a0 = a0 + acc[ai][bj][m][0]; a1 = a1 + acc[ai][bj][m][1];
;                     if (WT) st16_wt(xb + o, pack8(a0, a1)); else *(u32x4*)(xb + o) = pack8(a0, a1); s += hsq4(a0) + hsq4(a1); }
;                 s = red_fq(s); if (fq == 0) { if (WT) st4_wt(rsx + (size_t)row * 16 + u.pn * 4 + wc, s); else rsx[(size_t)row * 16 + u.pn * 4 + wc] = s; }
;                 asm volatile("" ::: "memory"); } }
.LBB0_1534:
	v_pk_add_f32 v[164:165], v[160:161], v[164:165]
	v_pk_add_f32 v[186:187], v[158:159], v[162:163]
	v_pk_add_f32 v[168:169], v[156:157], v[168:169]
	v_pk_add_f32 v[166:167], v[154:155], v[166:167]
	v_lshl_add_u64 v[162:163], v[188:189], 1, s[26:27]
	v_cvt_pk_bf16_f32 v154, v186, v187
	v_cvt_pk_bf16_f32 v155, v164, v165
	v_cvt_pk_bf16_f32 v156, v166, v167
	v_cvt_pk_bf16_f32 v157, v168, v169
	s_and_b64 vcc, exec, s[6:7]
	global_store_dwordx4 v[162:163], v[154:157], off sc1
	s_nop 1
	s_cbranch_vccnz .LBB0_1607
	global_load_dwordx4 v[158:161], v[184:185], off offset:528
	global_load_dwordx4 v[154:157], v[184:185], off offset:512
	s_waitcnt vmcnt(0)
	s_cbranch_execnz .LBB0_1537
.LBB0_1536:
	v_lshlrev_b32_e32 v154, 16, v126
	v_and_b32_e32 v155, 0xffff0000, v126
	v_lshlrev_b32_e32 v156, 16, v127
	v_and_b32_e32 v157, 0xffff0000, v127
	v_lshlrev_b32_e32 v158, 16, v128
	v_and_b32_e32 v159, 0xffff0000, v128
	v_lshlrev_b32_e32 v160, 16, v129
	v_and_b32_e32 v161, 0xffff0000, v129
.LBB0_1537:
	v_pk_add_f32 v[152:153], v[152:153], v[156:157]
	v_pk_add_f32 v[150:151], v[150:151], v[154:155]
	v_pk_add_f32 v[156:157], v[146:147], v[158:159]
	s_mov_b64 s[8:9], 0x100
	v_cvt_pk_bf16_f32 v146, v150, v151
	v_cvt_pk_bf16_f32 v147, v152, v153
	v_mul_f32_e32 v184, v187, v187
	v_mul_f32_e32 v165, v165, v165
	v_pk_add_f32 v[154:155], v[148:149], v[160:161]
	v_lshl_add_u64 v[158:159], v[162:163], 0, s[8:9]
	v_cvt_pk_bf16_f32 v148, v156, v157
	v_cvt_pk_bf16_f32 v149, v154, v155
	v_fmac_f32_e32 v184, v186, v186
	global_store_dwordx4 v[158:159], v[146:149], off sc1
	s_nop 1
	v_mul_f32_e32 v146, v151, v151
	v_mul_f32_e32 v147, v153, v153
	v_fmac_f32_e32 v165, v164, v164
	v_fmac_f32_e32 v146, v150, v150
	v_fmac_f32_e32 v147, v152, v152
	v_add_f32_e32 v164, v184, v165
	v_mul_f32_e32 v165, v167, v167
	v_add_f32_e32 v146, v146, v147
	v_mul_f32_e32 v147, v157, v157
	v_mul_f32_e32 v148, v155, v155
	v_fmac_f32_e32 v165, v166, v166
	v_mul_f32_e32 v166, v169, v169
	v_fmac_f32_e32 v147, v156, v156
	v_fmac_f32_e32 v148, v154, v154
	v_fmac_f32_e32 v166, v168, v168
	v_add_f32_e32 v147, v147, v148
	v_add_f32_e32 v165, v165, v166
	v_add_f32_e32 v146, v146, v147
	v_mbcnt_lo_u32_b32 v147, -1, 0
	v_mbcnt_hi_u32_b32 v147, -1, v147
	v_add_f32_e32 v164, v164, v165
	v_lshlrev_b32_e32 v147, 2, v147
	v_add_f32_e32 v146, v164, v146
	v_xor_b32_e32 v147, 64, v147
	ds_bpermute_b32 v147, v147, v146
	v_cmp_gt_u32_e64 s[8:9], 16, v193
	s_waitcnt lgkmcnt(0)
	v_add_f32_e32 v146, v146, v147
	v_mbcnt_lo_u32_b32 v147, -1, 0
	v_mbcnt_hi_u32_b32 v147, -1, v147
	s_nop 0
	v_lshlrev_b32_e32 v147, 2, v147
	v_xor_b32_e32 v147, 0x80, v147
	ds_bpermute_b32 v147, v147, v146
	s_and_saveexec_b64 s[58:59], s[8:9]
	s_cbranch_execz .LBB0_1539
	s_waitcnt lgkmcnt(0)
	v_add_f32_e32 v148, v146, v147
	v_lshlrev_b64 v[146:147], 6, v[180:181]
	s_lshl_b32 s12, s20, 2
	v_lshl_add_u64 v[146:147], s[28:29], 0, v[146:147]
	s_ashr_i32 s13, s12, 31
	v_lshl_add_u64 v[146:147], s[12:13], 2, v[146:147]
	s_lshl_b32 s56, s78, 2
	v_lshl_add_u64 v[146:147], v[146:147], 0, s[56:57]
	global_store_dword v[146:147], v148, off sc1
	s_nop 1
.LBB0_1539:
	s_or_b64 exec, exec, s[58:59]
	v_add3_u32 v154, v192, s45, 16
	v_ashrrev_i32_e32 v155, 31, v154
	s_waitcnt lgkmcnt(0)
	v_lshlrev_b64 v[146:147], 10, v[154:155]
	v_lshl_add_u64 v[146:147], v[146:147], 0, v[182:183]
	v_lshl_add_u64 v[160:161], v[146:147], 0, s[54:55]
	s_and_b64 vcc, exec, s[6:7]
	v_lshl_add_u64 v[156:157], v[160:161], 2, s[24:25]
	s_cbranch_vccnz .LBB0_1608
	global_load_dwordx4 v[150:153], v[156:157], off offset:16
	global_load_dwordx4 v[146:149], v[156:157], off
	s_waitcnt vmcnt(0)
	s_cbranch_execnz .LBB0_1542
.LBB0_1541:
	v_lshlrev_b32_e32 v146, 16, v110
	v_and_b32_e32 v147, 0xffff0000, v110
	v_lshlrev_b32_e32 v148, 16, v111
	v_and_b32_e32 v149, 0xffff0000, v111
	v_lshlrev_b32_e32 v150, 16, v112
	v_and_b32_e32 v151, 0xffff0000, v112
	v_lshlrev_b32_e32 v152, 16, v113
	v_and_b32_e32 v153, 0xffff0000, v113
.LBB0_1542:
	v_pk_add_f32 v[148:149], v[144:145], v[148:149]
	v_pk_add_f32 v[158:159], v[142:143], v[146:147]
	v_pk_add_f32 v[152:153], v[140:141], v[152:153]
	v_pk_add_f32 v[150:151], v[138:139], v[150:151]
	v_lshl_add_u64 v[146:147], v[160:161], 1, s[26:27]
	v_cvt_pk_bf16_f32 v138, v158, v159
	v_cvt_pk_bf16_f32 v139, v148, v149
	v_cvt_pk_bf16_f32 v140, v150, v151
	v_cvt_pk_bf16_f32 v141, v152, v153
	s_and_b64 vcc, exec, s[6:7]
	global_store_dwordx4 v[146:147], v[138:141], off sc1
	s_nop 1
	s_cbranch_vccnz .LBB0_1609
	global_load_dwordx4 v[142:145], v[156:157], off offset:528
	global_load_dwordx4 v[138:141], v[156:157], off offset:512
	s_waitcnt vmcnt(0)
	s_cbranch_execnz .LBB0_1545
.LBB0_1544:
	v_lshlrev_b32_e32 v138, 16, v106
	v_and_b32_e32 v139, 0xffff0000, v106
	v_lshlrev_b32_e32 v140, 16, v107
	v_and_b32_e32 v141, 0xffff0000, v107
	v_lshlrev_b32_e32 v142, 16, v108
	v_and_b32_e32 v143, 0xffff0000, v108
	v_lshlrev_b32_e32 v144, 16, v109
	v_and_b32_e32 v145, 0xffff0000, v109
; __device__ __forceinline__ void st16_wt(void* p, u32x4 v) { asm volatile("global_store_dwordx4 %0, %1, off sc1\n\ts_nop 1" :: "v"(p), "v"(v) : "memory"); }
; __device__ __forceinline__ void st16_wt(void* p, f32x4 v) { asm volatile("global_store_dwordx4 %0, %1, off sc1\n\ts_nop 1" :: "v"(p), "v"(v) : "memory"); }
; __device__ __forceinline__ void st4_wt(float* p, float v) { asm volatile("global_store_dword %0, %1, off sc1\n\ts_nop 1" :: "v"(p), "v"(v) : "memory"); }
; __device__ __forceinline__ u32x4 pack8(const f32x4& a, const f32x4& b) { u32x4 w; w.x = cvt_pk_bf16(a[0], a[1]); w.y = cvt_pk_bf16(a[2], a[3]); w.z = cvt_pk_bf16(b[0], b[1]); w.w = cvt_pk_bf16(b[2], b[3]); return w; }
; __device__ __forceinline__ float hsq4(const f32x4& v) { return (v[0] * v[0] + v[1] * v[1]) + (v[2] * v[2] + v[3] * v[3]); }
; __device__ __forceinline__ float red_fq(float s) { s += shfl_xor_(s, 16); s += shfl_xor_(s, 32); return s; }
; __device__ __forceinline__ f32x4 unpk_lo(unsigned a, unsigned b) { return (f32x4){__uint_as_float(a << 16), __uint_as_float(a & 0xffff0000u), __uint_as_float(b << 16), __uint_as_float(b & 0xffff0000u)}; }
;     __device__ __forceinline__ void operator()(const f32x4 (&acc)[2][2][4][2], const Unit& u, int wr, int wc, int fr, int fq) const {
;     ...
;             for (int m = 0; m < 4; ++m) { const int row = u.pm * BM + ai * HALF + wr * 64 + m * 16 + fr;
;                 float s = 0.f;
; #pragma unroll
;                 for (int bj = 0; bj < 2; ++bj) { const size_t o = (size_t)row * DM + u.pn * 256 + bj * HALF + cb;
;                     f32x4 a0, a1;
;                     if (xin_f32) { a0 = *(const f32x4*)(xin_f32 + o); a1 = *(const f32x4*)(xin_f32 + o + 4); }
;                     else { const u32x4 w = rw[m][bj]; a0 = unpk_lo(w.x, w.y); a1 = unpk_lo(w.z, w.w); }
;                     a0 = a0 + acc[ai][bj][m][0]; a1 = a1 + acc[ai][bj][m][1];
;                     if (WT) st16_wt(xb + o, pack8(a0, a1)); else *(u32x4*)(xb + o) = pack8(a0, a1); s += hsq4(a0) + hsq4(a1); }
;                 s = red_fq(s); if (fq == 0) { if (WT) st4_wt(rsx + (size_t)row * 16 + u.pn * 4 + wc, s); else rsx[(size_t)row * 16 + u.pn * 4 + wc] = s; }
;                 asm volatile("" ::: "memory"); } }
.LBB0_1545:
	v_pk_add_f32 v[132:133], v[132:133], v[140:141]
	v_pk_add_f32 v[130:131], v[130:131], v[138:139]
	v_pk_add_f32 v[140:141], v[122:123], v[142:143]
	s_mov_b64 s[12:13], 0x100
	v_cvt_pk_bf16_f32 v122, v130, v131
	v_cvt_pk_bf16_f32 v123, v132, v133
	v_mul_f32_e32 v156, v159, v159
	v_mul_f32_e32 v149, v149, v149
	v_pk_add_f32 v[138:139], v[124:125], v[144:145]
	v_lshl_add_u64 v[142:143], v[146:147], 0, s[12:13]
	v_cvt_pk_bf16_f32 v124, v140, v141
	v_cvt_pk_bf16_f32 v125, v138, v139
	v_fmac_f32_e32 v156, v158, v158
	global_store_dwordx4 v[142:143], v[122:125], off sc1
	s_nop 1
	v_mul_f32_e32 v122, v131, v131
	v_mul_f32_e32 v123, v133, v133
	v_fmac_f32_e32 v149, v148, v148
	v_fmac_f32_e32 v122, v130, v130
	v_fmac_f32_e32 v123, v132, v132
	v_add_f32_e32 v148, v156, v149
	v_mul_f32_e32 v149, v151, v151
	v_add_f32_e32 v122, v122, v123
	v_mul_f32_e32 v123, v141, v141
	v_mul_f32_e32 v124, v139, v139
	v_fmac_f32_e32 v149, v150, v150
	v_mul_f32_e32 v150, v153, v153
	v_fmac_f32_e32 v123, v140, v140
	v_fmac_f32_e32 v124, v138, v138
	v_fmac_f32_e32 v150, v152, v152
	v_add_f32_e32 v123, v123, v124
	v_add_f32_e32 v149, v149, v150
	v_add_f32_e32 v122, v122, v123
	v_mbcnt_lo_u32_b32 v123, -1, 0
	v_mbcnt_hi_u32_b32 v123, -1, v123
	v_add_f32_e32 v148, v148, v149
	v_lshlrev_b32_e32 v123, 2, v123
	v_add_f32_e32 v122, v148, v122
	v_xor_b32_e32 v123, 64, v123
	ds_bpermute_b32 v123, v123, v122
	s_waitcnt lgkmcnt(0)
	v_add_f32_e32 v122, v122, v123
	v_mbcnt_lo_u32_b32 v123, -1, 0
	v_mbcnt_hi_u32_b32 v123, -1, v123
	s_nop 0
	v_lshlrev_b32_e32 v123, 2, v123
	v_xor_b32_e32 v123, 0x80, v123
	ds_bpermute_b32 v123, v123, v122
	s_and_saveexec_b64 s[58:59], s[8:9]
	s_cbranch_execz .LBB0_1547
	s_waitcnt lgkmcnt(0)
	v_add_f32_e32 v124, v122, v123
	v_lshlrev_b64 v[122:123], 6, v[154:155]
	s_lshl_b32 s12, s20, 2
	v_lshl_add_u64 v[122:123], s[28:29], 0, v[122:123]
	s_ashr_i32 s13, s12, 31
	v_lshl_add_u64 v[122:123], s[12:13], 2, v[122:123]
	s_lshl_b32 s56, s78, 2
	v_lshl_add_u64 v[122:123], v[122:123], 0, s[56:57]
	global_store_dword v[122:123], v124, off sc1
	s_nop 1
.LBB0_1547:
	s_or_b64 exec, exec, s[58:59]
	v_add3_u32 v138, v192, s45, 32
	v_ashrrev_i32_e32 v139, 31, v138
	s_waitcnt lgkmcnt(0)
	v_lshlrev_b64 v[122:123], 10, v[138:139]
	v_lshl_add_u64 v[122:123], v[122:123], 0, v[182:183]
	v_lshl_add_u64 v[144:145], v[122:123], 0, s[54:55]
	s_and_b64 vcc, exec, s[6:7]
	v_lshl_add_u64 v[140:141], v[144:145], 2, s[24:25]
	s_cbranch_vccnz .LBB0_1610
	global_load_dwordx4 v[130:133], v[140:141], off offset:16
	global_load_dwordx4 v[122:125], v[140:141], off
	s_waitcnt vmcnt(0)
	s_cbranch_execnz .LBB0_1550
.LBB0_1549:
	v_lshlrev_b32_e32 v122, 16, v90
	v_and_b32_e32 v123, 0xffff0000, v90
	v_lshlrev_b32_e32 v124, 16, v91
	v_and_b32_e32 v125, 0xffff0000, v91
	v_lshlrev_b32_e32 v130, 16, v92
	v_and_b32_e32 v131, 0xffff0000, v92
	v_lshlrev_b32_e32 v132, 16, v93
	v_and_b32_e32 v133, 0xffff0000, v93
.LBB0_1550:
	v_pk_add_f32 v[124:125], v[120:121], v[124:125]
	v_pk_add_f32 v[142:143], v[118:119], v[122:123]
	v_pk_add_f32 v[132:133], v[116:117], v[132:133]
	v_pk_add_f32 v[130:131], v[114:115], v[130:131]
	v_lshl_add_u64 v[122:123], v[144:145], 1, s[26:27]
	v_cvt_pk_bf16_f32 v114, v142, v143
	v_cvt_pk_bf16_f32 v115, v124, v125
	v_cvt_pk_bf16_f32 v116, v130, v131
	v_cvt_pk_bf16_f32 v117, v132, v133
	s_and_b64 vcc, exec, s[6:7]
	global_store_dwordx4 v[122:123], v[114:117], off sc1
	s_nop 1
	s_cbranch_vccnz .LBB0_1611
	global_load_dwordx4 v[118:121], v[140:141], off offset:528
	global_load_dwordx4 v[114:117], v[140:141], off offset:512
	s_waitcnt vmcnt(0)
	s_cbranch_execnz .LBB0_1553
.LBB0_1552:
	v_lshlrev_b32_e32 v114, 16, v82
	v_and_b32_e32 v115, 0xffff0000, v82
	v_lshlrev_b32_e32 v116, 16, v83
	v_and_b32_e32 v117, 0xffff0000, v83
	v_lshlrev_b32_e32 v118, 16, v84
	v_and_b32_e32 v119, 0xffff0000, v84
	v_lshlrev_b32_e32 v120, 16, v85
	v_and_b32_e32 v121, 0xffff0000, v85
; __device__ __forceinline__ void st16_wt(void* p, u32x4 v) { asm volatile("global_store_dwordx4 %0, %1, off sc1\n\ts_nop 1" :: "v"(p), "v"(v) : "memory"); }
; __device__ __forceinline__ void st16_wt(void* p, f32x4 v) { asm volatile("global_store_dwordx4 %0, %1, off sc1\n\ts_nop 1" :: "v"(p), "v"(v) : "memory"); }
; __device__ __forceinline__ void st4_wt(float* p, float v) { asm volatile("global_store_dword %0, %1, off sc1\n\ts_nop 1" :: "v"(p), "v"(v) : "memory"); }
; __device__ __forceinline__ u32x4 pack8(const f32x4& a, const f32x4& b) { u32x4 w; w.x = cvt_pk_bf16(a[0], a[1]); w.y = cvt_pk_bf16(a[2], a[3]); w.z = cvt_pk_bf16(b[0], b[1]); w.w = cvt_pk_bf16(b[2], b[3]); return w; }
; __device__ __forceinline__ float hsq4(const f32x4& v) { return (v[0] * v[0] + v[1] * v[1]) + (v[2] * v[2] + v[3] * v[3]); }
; __device__ __forceinline__ float red_fq(float s) { s += shfl_xor_(s, 16); s += shfl_xor_(s, 32); return s; }
; __device__ __forceinline__ f32x4 unpk_lo(unsigned a, unsigned b) { return (f32x4){__uint_as_float(a << 16), __uint_as_float(a & 0xffff0000u), __uint_as_float(b << 16), __uint_as_float(b & 0xffff0000u)}; }
;     __device__ __forceinline__ void operator()(const f32x4 (&acc)[2][2][4][2], const Unit& u, int wr, int wc, int fr, int fq) const {
;     ...
;             for (int m = 0; m < 4; ++m) { const int row = u.pm * BM + ai * HALF + wr * 64 + m * 16 + fr;
;                 float s = 0.f;
; #pragma unroll
;                 for (int bj = 0; bj < 2; ++bj) { const size_t o = (size_t)row * DM + u.pn * 256 + bj * HALF + cb;
;                     f32x4 a0, a1;
;                     if (xin_f32) { a0 = *(const f32x4*)(xin_f32 + o); a1 = *(const f32x4*)(xin_f32 + o + 4); }
;                     else { const u32x4 w = rw[m][bj]; a0 = unpk_lo(w.x, w.y); a1 = unpk_lo(w.z, w.w); }
;                     a0 = a0 + acc[ai][bj][m][0]; a1 = a1 + acc[ai][bj][m][1];
;                     if (WT) st16_wt(xb + o, pack8(a0, a1)); else *(u32x4*)(xb + o) = pack8(a0, a1); s += hsq4(a0) + hsq4(a1); }
;                 s = red_fq(s); if (fq == 0) { if (WT) st4_wt(rsx + (size_t)row * 16 + u.pn * 4 + wc, s); else rsx[(size_t)row * 16 + u.pn * 4 + wc] = s; }
;                 asm volatile("" ::: "memory"); } }
.LBB0_1553:
	v_pk_add_f32 v[104:105], v[104:105], v[116:117]
	v_pk_add_f32 v[102:103], v[102:103], v[114:115]
	v_pk_add_f32 v[116:117], v[98:99], v[118:119]
	s_mov_b64 s[12:13], 0x100
	v_cvt_pk_bf16_f32 v98, v102, v103
	v_cvt_pk_bf16_f32 v99, v104, v105
	v_mul_f32_e32 v140, v143, v143
	v_mul_f32_e32 v125, v125, v125
	v_pk_add_f32 v[114:115], v[100:101], v[120:121]
	v_lshl_add_u64 v[118:119], v[122:123], 0, s[12:13]
	v_cvt_pk_bf16_f32 v100, v116, v117
	v_cvt_pk_bf16_f32 v101, v114, v115
	v_fmac_f32_e32 v140, v142, v142
	global_store_dwordx4 v[118:119], v[98:101], off sc1
	s_nop 1
	v_mul_f32_e32 v98, v103, v103
	v_mul_f32_e32 v99, v105, v105
	v_fmac_f32_e32 v125, v124, v124
	v_fmac_f32_e32 v98, v102, v102
	v_fmac_f32_e32 v99, v104, v104
	v_add_f32_e32 v124, v140, v125
	v_mul_f32_e32 v125, v131, v131
	v_add_f32_e32 v98, v98, v99
	v_mul_f32_e32 v99, v117, v117
	v_mul_f32_e32 v100, v115, v115
	v_fmac_f32_e32 v125, v130, v130
	v_mul_f32_e32 v130, v133, v133
	v_fmac_f32_e32 v99, v116, v116
	v_fmac_f32_e32 v100, v114, v114
	v_fmac_f32_e32 v130, v132, v132
	v_add_f32_e32 v99, v99, v100
	v_add_f32_e32 v125, v125, v130
	v_add_f32_e32 v98, v98, v99
	v_mbcnt_lo_u32_b32 v99, -1, 0
	v_mbcnt_hi_u32_b32 v99, -1, v99
	v_add_f32_e32 v124, v124, v125
	v_lshlrev_b32_e32 v99, 2, v99
	v_add_f32_e32 v98, v124, v98
	v_xor_b32_e32 v99, 64, v99
	ds_bpermute_b32 v99, v99, v98
	s_waitcnt lgkmcnt(0)
	v_add_f32_e32 v98, v98, v99
	v_mbcnt_lo_u32_b32 v99, -1, 0
	v_mbcnt_hi_u32_b32 v99, -1, v99
	s_nop 0
	v_lshlrev_b32_e32 v99, 2, v99
	v_xor_b32_e32 v99, 0x80, v99
	ds_bpermute_b32 v99, v99, v98
	s_and_saveexec_b64 s[58:59], s[8:9]
	s_cbranch_execz .LBB0_1555
	s_waitcnt lgkmcnt(0)
	v_add_f32_e32 v100, v98, v99
	v_lshlrev_b64 v[98:99], 6, v[138:139]
	s_lshl_b32 s12, s20, 2
	v_lshl_add_u64 v[98:99], s[28:29], 0, v[98:99]
	s_ashr_i32 s13, s12, 31
	v_lshl_add_u64 v[98:99], s[12:13], 2, v[98:99]
	s_lshl_b32 s56, s78, 2
	v_lshl_add_u64 v[98:99], v[98:99], 0, s[56:57]
	global_store_dword v[98:99], v100, off sc1
	s_nop 1
.LBB0_1555:
	s_or_b64 exec, exec, s[58:59]
	v_add3_u32 v114, v192, s45, 48
	v_ashrrev_i32_e32 v115, 31, v114
	s_waitcnt lgkmcnt(0)
	v_lshlrev_b64 v[98:99], 10, v[114:115]
	v_lshl_add_u64 v[98:99], v[98:99], 0, v[182:183]
	v_lshl_add_u64 v[120:121], v[98:99], 0, s[54:55]
	s_and_b64 vcc, exec, s[6:7]
	v_lshl_add_u64 v[116:117], v[120:121], 2, s[24:25]
	s_cbranch_vccnz .LBB0_1612
	global_load_dwordx4 v[102:105], v[116:117], off offset:16
	global_load_dwordx4 v[98:101], v[116:117], off
	s_waitcnt vmcnt(0)
	s_cbranch_execnz .LBB0_1558
.LBB0_1557:
	v_lshlrev_b32_e32 v98, 16, v70
	v_and_b32_e32 v99, 0xffff0000, v70
	v_lshlrev_b32_e32 v100, 16, v71
	v_and_b32_e32 v101, 0xffff0000, v71
	v_lshlrev_b32_e32 v102, 16, v72
	v_and_b32_e32 v103, 0xffff0000, v72
	v_lshlrev_b32_e32 v104, 16, v73
	v_and_b32_e32 v105, 0xffff0000, v73
.LBB0_1558:
	v_pk_add_f32 v[100:101], v[96:97], v[100:101]
	v_pk_add_f32 v[118:119], v[94:95], v[98:99]
	v_pk_add_f32 v[104:105], v[88:89], v[104:105]
	v_pk_add_f32 v[102:103], v[86:87], v[102:103]
	v_lshl_add_u64 v[98:99], v[120:121], 1, s[26:27]
	v_cvt_pk_bf16_f32 v86, v118, v119
	v_cvt_pk_bf16_f32 v87, v100, v101
	v_cvt_pk_bf16_f32 v88, v102, v103
	v_cvt_pk_bf16_f32 v89, v104, v105
	s_and_b64 vcc, exec, s[6:7]
	global_store_dwordx4 v[98:99], v[86:89], off sc1
	s_nop 1
	s_cbranch_vccnz .LBB0_1613
	global_load_dwordx4 v[94:97], v[116:117], off offset:528
	global_load_dwordx4 v[86:89], v[116:117], off offset:512
	s_waitcnt vmcnt(0)
	s_cbranch_execnz .LBB0_1561
.LBB0_1560:
	v_lshlrev_b32_e32 v86, 16, v66
	v_and_b32_e32 v87, 0xffff0000, v66
	v_lshlrev_b32_e32 v88, 16, v67
	v_and_b32_e32 v89, 0xffff0000, v67
	v_lshlrev_b32_e32 v94, 16, v68
	v_and_b32_e32 v95, 0xffff0000, v68
	v_lshlrev_b32_e32 v96, 16, v69
	v_and_b32_e32 v97, 0xffff0000, v69
.LBB0_1561:
	v_pk_add_f32 v[80:81], v[80:81], v[88:89]
	v_pk_add_f32 v[78:79], v[78:79], v[86:87]
	v_pk_add_f32 v[88:89], v[74:75], v[94:95]
	s_mov_b64 s[12:13], 0x100
	v_cvt_pk_bf16_f32 v74, v78, v79
	v_cvt_pk_bf16_f32 v75, v80, v81
	v_mul_f32_e32 v116, v119, v119
	v_mul_f32_e32 v101, v101, v101
	v_pk_add_f32 v[86:87], v[76:77], v[96:97]
	v_lshl_add_u64 v[94:95], v[98:99], 0, s[12:13]
	v_cvt_pk_bf16_f32 v76, v88, v89
	v_cvt_pk_bf16_f32 v77, v86, v87
	v_fmac_f32_e32 v116, v118, v118
	global_store_dwordx4 v[94:95], v[74:77], off sc1
	s_nop 1
	v_mul_f32_e32 v74, v79, v79
	v_mul_f32_e32 v75, v81, v81
	v_fmac_f32_e32 v101, v100, v100
	v_fmac_f32_e32 v74, v78, v78
	v_fmac_f32_e32 v75, v80, v80
	v_add_f32_e32 v100, v116, v101
	v_mul_f32_e32 v101, v103, v103
	v_add_f32_e32 v74, v74, v75
	v_mul_f32_e32 v75, v89, v89
	v_mul_f32_e32 v76, v87, v87
	v_fmac_f32_e32 v101, v102, v102
	v_mul_f32_e32 v102, v105, v105
	v_fmac_f32_e32 v75, v88, v88
	v_fmac_f32_e32 v76, v86, v86
	v_fmac_f32_e32 v102, v104, v104
	v_add_f32_e32 v75, v75, v76
	v_add_f32_e32 v101, v101, v102
	v_add_f32_e32 v74, v74, v75
	v_mbcnt_lo_u32_b32 v75, -1, 0
	v_mbcnt_hi_u32_b32 v75, -1, v75
	v_add_f32_e32 v100, v100, v101
	v_lshlrev_b32_e32 v75, 2, v75
	v_add_f32_e32 v74, v100, v74
	v_xor_b32_e32 v75, 64, v75
	ds_bpermute_b32 v75, v75, v74
	s_waitcnt lgkmcnt(0)
	v_add_f32_e32 v74, v74, v75
	v_mbcnt_lo_u32_b32 v75, -1, 0
	v_mbcnt_hi_u32_b32 v75, -1, v75
	s_nop 0
	v_lshlrev_b32_e32 v75, 2, v75
	v_xor_b32_e32 v75, 0x80, v75
	ds_bpermute_b32 v75, v75, v74
	s_and_saveexec_b64 s[58:59], s[8:9]
	s_cbranch_execz .LBB0_1563
	s_waitcnt lgkmcnt(0)
	v_add_f32_e32 v76, v74, v75
	v_lshlrev_b64 v[74:75], 6, v[114:115]
	s_lshl_b32 s12, s20, 2
	v_lshl_add_u64 v[74:75], s[28:29], 0, v[74:75]
	s_ashr_i32 s13, s12, 31
	v_lshl_add_u64 v[74:75], s[12:13], 2, v[74:75]
	s_lshl_b32 s56, s78, 2
	v_lshl_add_u64 v[74:75], v[74:75], 0, s[56:57]
	global_store_dword v[74:75], v76, off sc1
	s_nop 1

; __device__ __forceinline__ void st16_wt(void* p, u32x4 v) { asm volatile("global_store_dwordx4 %0, %1, off sc1\n\ts_nop 1" :: "v"(p), "v"(v) : "memory"); }
; __device__ __forceinline__ void st16_wt(void* p, f32x4 v) { asm volatile("global_store_dwordx4 %0, %1, off sc1\n\ts_nop 1" :: "v"(p), "v"(v) : "memory"); }
; __device__ __forceinline__ u32x4 pack8(const f32x4& a, const f32x4& b) { u32x4 w; w.x = cvt_pk_bf16(a[0], a[1]); w.y = cvt_pk_bf16(a[2], a[3]); w.z = cvt_pk_bf16(b[0], b[1]); w.w = cvt_pk_bf16(b[2], b[3]); return w; }
; __device__ __forceinline__ float hsq4(const f32x4& v) { return (v[0] * v[0] + v[1] * v[1]) + (v[2] * v[2] + v[3] * v[3]); }
; __device__ __forceinline__ f32x4 unpk_lo(unsigned a, unsigned b) { return (f32x4){__uint_as_float(a << 16), __uint_as_float(a & 0xffff0000u), __uint_as_float(b << 16), __uint_as_float(b & 0xffff0000u)}; }
;     __device__ __forceinline__ void operator()(const f32x4 (&acc)[2][2][4][2], const Unit& u, int wr, int wc, int fr, int fq) const {
;     ...
;             for (int m = 0; m < 4; ++m) { const int row = u.pm * BM + ai * HALF + wr * 64 + m * 16 + fr;
;                 float s = 0.f;
; #pragma unroll
;                 for (int bj = 0; bj < 2; ++bj) { const size_t o = (size_t)row * DM + u.pn * 256 + bj * HALF + cb;
;                     f32x4 a0, a1;
;                     if (xin_f32) { a0 = *(const f32x4*)(xin_f32 + o); a1 = *(const f32x4*)(xin_f32 + o + 4); }
;                     else { const u32x4 w = rw[m][bj]; a0 = unpk_lo(w.x, w.y); a1 = unpk_lo(w.z, w.w); }
;                     a0 = a0 + acc[ai][bj][m][0]; a1 = a1 + acc[ai][bj][m][1];
;                     if (WT) st16_wt(xb + o, pack8(a0, a1)); else *(u32x4*)(xb + o) = pack8(a0, a1); s += hsq4(a0) + hsq4(a1); }
.LBB0_1566:
	s_waitcnt lgkmcnt(0)
	v_lshlrev_b64 v[74:75], 10, v[86:87]
	v_lshl_add_u64 v[74:75], v[74:75], 0, v[182:183]
	v_lshl_add_u64 v[96:97], v[74:75], 0, s[54:55]
	s_and_b64 vcc, exec, s[6:7]
	v_lshl_add_u64 v[88:89], v[96:97], 2, s[24:25]
	s_cbranch_vccnz .LBB0_1615
	global_load_dwordx4 v[78:81], v[88:89], off offset:16
	global_load_dwordx4 v[74:77], v[88:89], off
	s_waitcnt vmcnt(0)
	s_cbranch_execnz .LBB0_1569

; __device__ __forceinline__ void st16_wt(void* p, u32x4 v) { asm volatile("global_store_dwordx4 %0, %1, off sc1\n\ts_nop 1" :: "v"(p), "v"(v) : "memory"); }
; __device__ __forceinline__ void st16_wt(void* p, f32x4 v) { asm volatile("global_store_dwordx4 %0, %1, off sc1\n\ts_nop 1" :: "v"(p), "v"(v) : "memory"); }
; __device__ __forceinline__ void st4_wt(float* p, float v) { asm volatile("global_store_dword %0, %1, off sc1\n\ts_nop 1" :: "v"(p), "v"(v) : "memory"); }
; __device__ __forceinline__ u32x4 pack8(const f32x4& a, const f32x4& b) { u32x4 w; w.x = cvt_pk_bf16(a[0], a[1]); w.y = cvt_pk_bf16(a[2], a[3]); w.z = cvt_pk_bf16(b[0], b[1]); w.w = cvt_pk_bf16(b[2], b[3]); return w; }
; __device__ __forceinline__ float hsq4(const f32x4& v) { return (v[0] * v[0] + v[1] * v[1]) + (v[2] * v[2] + v[3] * v[3]); }
; __device__ __forceinline__ float red_fq(float s) { s += shfl_xor_(s, 16); s += shfl_xor_(s, 32); return s; }
; __device__ __forceinline__ f32x4 unpk_lo(unsigned a, unsigned b) { return (f32x4){__uint_as_float(a << 16), __uint_as_float(a & 0xffff0000u), __uint_as_float(b << 16), __uint_as_float(b & 0xffff0000u)}; }
;     __device__ __forceinline__ void operator()(const f32x4 (&acc)[2][2][4][2], const Unit& u, int wr, int wc, int fr, int fq) const {
;     ...
;             for (int m = 0; m < 4; ++m) { const int row = u.pm * BM + ai * HALF + wr * 64 + m * 16 + fr;
;                 float s = 0.f;
; #pragma unroll
;                 for (int bj = 0; bj < 2; ++bj) { const size_t o = (size_t)row * DM + u.pn * 256 + bj * HALF + cb;
;                     f32x4 a0, a1;
;                     if (xin_f32) { a0 = *(const f32x4*)(xin_f32 + o); a1 = *(const f32x4*)(xin_f32 + o + 4); }
;                     else { const u32x4 w = rw[m][bj]; a0 = unpk_lo(w.x, w.y); a1 = unpk_lo(w.z, w.w); }
;                     a0 = a0 + acc[ai][bj][m][0]; a1 = a1 + acc[ai][bj][m][1];
;                     if (WT) st16_wt(xb + o, pack8(a0, a1)); else *(u32x4*)(xb + o) = pack8(a0, a1); s += hsq4(a0) + hsq4(a1); }
;                 s = red_fq(s); if (fq == 0) { if (WT) st4_wt(rsx + (size_t)row * 16 + u.pn * 4 + wc, s); else rsx[(size_t)row * 16 + u.pn * 4 + wc] = s; }
;                 asm volatile("" ::: "memory"); } }
.LBB0_1569:
	v_pk_add_f32 v[76:77], v[64:65], v[76:77]
	v_pk_add_f32 v[94:95], v[62:63], v[74:75]
	v_pk_add_f32 v[80:81], v[60:61], v[80:81]
	v_pk_add_f32 v[78:79], v[58:59], v[78:79]
	v_lshl_add_u64 v[74:75], v[96:97], 1, s[26:27]
	v_cvt_pk_bf16_f32 v58, v94, v95
	v_cvt_pk_bf16_f32 v59, v76, v77
	v_cvt_pk_bf16_f32 v60, v78, v79
	v_cvt_pk_bf16_f32 v61, v80, v81
	s_and_b64 vcc, exec, s[6:7]
	global_store_dwordx4 v[74:75], v[58:61], off sc1
	s_nop 1
	s_cbranch_vccnz .LBB0_1616
	global_load_dwordx4 v[62:65], v[88:89], off offset:528
	global_load_dwordx4 v[58:61], v[88:89], off offset:512
	s_waitcnt vmcnt(0)
	s_cbranch_execnz .LBB0_1572
.LBB0_1571:
	v_lshlrev_b32_e32 v58, 16, v126
	v_and_b32_e32 v59, 0xffff0000, v126
	v_lshlrev_b32_e32 v60, 16, v127
	v_and_b32_e32 v61, 0xffff0000, v127
	v_lshlrev_b32_e32 v62, 16, v128
	v_and_b32_e32 v63, 0xffff0000, v128
	v_lshlrev_b32_e32 v64, 16, v129
	v_and_b32_e32 v65, 0xffff0000, v129
.LBB0_1572:
	v_pk_add_f32 v[56:57], v[56:57], v[60:61]
	v_pk_add_f32 v[54:55], v[54:55], v[58:59]
	v_pk_add_f32 v[60:61], v[50:51], v[62:63]
	s_mov_b64 s[12:13], 0x100
	v_cvt_pk_bf16_f32 v50, v54, v55
	v_cvt_pk_bf16_f32 v51, v56, v57
	v_mul_f32_e32 v88, v95, v95
	v_mul_f32_e32 v77, v77, v77
	v_pk_add_f32 v[58:59], v[52:53], v[64:65]
	v_lshl_add_u64 v[62:63], v[74:75], 0, s[12:13]
	v_cvt_pk_bf16_f32 v52, v60, v61
	v_cvt_pk_bf16_f32 v53, v58, v59
	v_fmac_f32_e32 v88, v94, v94
	global_store_dwordx4 v[62:63], v[50:53], off sc1
	s_nop 1
	v_mul_f32_e32 v50, v55, v55
	v_mul_f32_e32 v51, v57, v57
	v_fmac_f32_e32 v77, v76, v76
	v_fmac_f32_e32 v50, v54, v54
	v_fmac_f32_e32 v51, v56, v56
	v_add_f32_e32 v76, v88, v77
	v_mul_f32_e32 v77, v79, v79
	v_add_f32_e32 v50, v50, v51
	v_mul_f32_e32 v51, v61, v61
	v_mul_f32_e32 v52, v59, v59
	v_fmac_f32_e32 v77, v78, v78
	v_mul_f32_e32 v78, v81, v81
	v_fmac_f32_e32 v51, v60, v60
	v_fmac_f32_e32 v52, v58, v58
	v_fmac_f32_e32 v78, v80, v80
	v_add_f32_e32 v51, v51, v52
	v_add_f32_e32 v77, v77, v78
	v_add_f32_e32 v50, v50, v51
	v_mbcnt_lo_u32_b32 v51, -1, 0
	v_mbcnt_hi_u32_b32 v51, -1, v51
	v_add_f32_e32 v76, v76, v77
	v_lshlrev_b32_e32 v51, 2, v51
	v_add_f32_e32 v50, v76, v50
	v_xor_b32_e32 v51, 64, v51
	ds_bpermute_b32 v51, v51, v50
	s_waitcnt lgkmcnt(0)
	v_add_f32_e32 v50, v50, v51
	v_mbcnt_lo_u32_b32 v51, -1, 0
	v_mbcnt_hi_u32_b32 v51, -1, v51
	s_nop 0
	v_lshlrev_b32_e32 v51, 2, v51
	v_xor_b32_e32 v51, 0x80, v51
	ds_bpermute_b32 v51, v51, v50
	s_and_saveexec_b64 s[58:59], s[8:9]
	s_cbranch_execz .LBB0_1574
	s_waitcnt lgkmcnt(0)
	v_add_f32_e32 v52, v50, v51
	v_lshlrev_b64 v[50:51], 6, v[86:87]
	s_lshl_b32 s12, s20, 2
	v_lshl_add_u64 v[50:51], s[28:29], 0, v[50:51]
	s_ashr_i32 s13, s12, 31
	v_lshl_add_u64 v[50:51], s[12:13], 2, v[50:51]
	s_lshl_b32 s56, s78, 2
	v_lshl_add_u64 v[50:51], v[50:51], 0, s[56:57]
	global_store_dword v[50:51], v52, off sc1
	s_nop 1
.LBB0_1574:
	s_or_b64 exec, exec, s[58:59]
	v_add_u32_e32 v58, 0x90, v180
	v_ashrrev_i32_e32 v59, 31, v58
	s_waitcnt lgkmcnt(0)
	v_lshlrev_b64 v[50:51], 10, v[58:59]
	v_lshl_add_u64 v[50:51], v[50:51], 0, v[182:183]
	v_lshl_add_u64 v[64:65], v[50:51], 0, s[54:55]
	s_and_b64 vcc, exec, s[6:7]
	v_lshl_add_u64 v[60:61], v[64:65], 2, s[24:25]
	s_cbranch_vccnz .LBB0_1617
	global_load_dwordx4 v[54:57], v[60:61], off offset:16
	global_load_dwordx4 v[50:53], v[60:61], off
	s_waitcnt vmcnt(0)
	s_cbranch_execnz .LBB0_1577
.LBB0_1576:
	v_lshlrev_b32_e32 v50, 16, v110
	v_and_b32_e32 v51, 0xffff0000, v110
	v_lshlrev_b32_e32 v52, 16, v111
	v_and_b32_e32 v53, 0xffff0000, v111
	v_lshlrev_b32_e32 v54, 16, v112
	v_and_b32_e32 v55, 0xffff0000, v112
	v_lshlrev_b32_e32 v56, 16, v113
	v_and_b32_e32 v57, 0xffff0000, v113
.LBB0_1577:
	v_pk_add_f32 v[52:53], v[48:49], v[52:53]
	v_pk_add_f32 v[62:63], v[46:47], v[50:51]
	v_pk_add_f32 v[56:57], v[44:45], v[56:57]
	v_pk_add_f32 v[54:55], v[42:43], v[54:55]
	v_lshl_add_u64 v[50:51], v[64:65], 1, s[26:27]
	v_cvt_pk_bf16_f32 v42, v62, v63
	v_cvt_pk_bf16_f32 v43, v52, v53
	v_cvt_pk_bf16_f32 v44, v54, v55
	v_cvt_pk_bf16_f32 v45, v56, v57
	s_and_b64 vcc, exec, s[6:7]
	global_store_dwordx4 v[50:51], v[42:45], off sc1
	s_nop 1
	s_cbranch_vccnz .LBB0_1618
	global_load_dwordx4 v[46:49], v[60:61], off offset:528
	global_load_dwordx4 v[42:45], v[60:61], off offset:512
	s_waitcnt vmcnt(0)
	s_cbranch_execnz .LBB0_1580
.LBB0_1579:
	v_lshlrev_b32_e32 v42, 16, v106
	v_and_b32_e32 v43, 0xffff0000, v106
	v_lshlrev_b32_e32 v44, 16, v107
	v_and_b32_e32 v45, 0xffff0000, v107
	v_lshlrev_b32_e32 v46, 16, v108
	v_and_b32_e32 v47, 0xffff0000, v108
	v_lshlrev_b32_e32 v48, 16, v109
	v_and_b32_e32 v49, 0xffff0000, v109
.LBB0_1580:
	v_pk_add_f32 v[40:41], v[40:41], v[44:45]
	v_pk_add_f32 v[38:39], v[38:39], v[42:43]
	v_pk_add_f32 v[44:45], v[34:35], v[46:47]
	s_mov_b64 s[12:13], 0x100
	v_cvt_pk_bf16_f32 v34, v38, v39
	v_cvt_pk_bf16_f32 v35, v40, v41
	v_mul_f32_e32 v60, v63, v63
	v_mul_f32_e32 v53, v53, v53
	v_pk_add_f32 v[42:43], v[36:37], v[48:49]
	v_lshl_add_u64 v[46:47], v[50:51], 0, s[12:13]
	v_cvt_pk_bf16_f32 v36, v44, v45
	v_cvt_pk_bf16_f32 v37, v42, v43
	v_fmac_f32_e32 v60, v62, v62
	global_store_dwordx4 v[46:47], v[34:37], off sc1
	s_nop 1
	v_mul_f32_e32 v34, v39, v39
	v_mul_f32_e32 v35, v41, v41
	v_fmac_f32_e32 v53, v52, v52
	v_fmac_f32_e32 v34, v38, v38
	v_fmac_f32_e32 v35, v40, v40
	v_add_f32_e32 v52, v60, v53
	v_mul_f32_e32 v53, v55, v55
	v_add_f32_e32 v34, v34, v35
	v_mul_f32_e32 v35, v45, v45
	v_mul_f32_e32 v36, v43, v43
	v_fmac_f32_e32 v53, v54, v54
	v_mul_f32_e32 v54, v57, v57
	v_fmac_f32_e32 v35, v44, v44
	v_fmac_f32_e32 v36, v42, v42
	v_fmac_f32_e32 v54, v56, v56
	v_add_f32_e32 v35, v35, v36
	v_add_f32_e32 v53, v53, v54
	v_add_f32_e32 v34, v34, v35
	v_mbcnt_lo_u32_b32 v35, -1, 0
	v_mbcnt_hi_u32_b32 v35, -1, v35
	v_add_f32_e32 v52, v52, v53
	v_lshlrev_b32_e32 v35, 2, v35
	v_add_f32_e32 v34, v52, v34
	v_xor_b32_e32 v35, 64, v35
	ds_bpermute_b32 v35, v35, v34
	s_waitcnt lgkmcnt(0)
	v_add_f32_e32 v34, v34, v35
	v_mbcnt_lo_u32_b32 v35, -1, 0
	v_mbcnt_hi_u32_b32 v35, -1, v35
	s_nop 0
	v_lshlrev_b32_e32 v35, 2, v35
	v_xor_b32_e32 v35, 0x80, v35
	ds_bpermute_b32 v35, v35, v34
	s_and_saveexec_b64 s[58:59], s[8:9]
	s_cbranch_execz .LBB0_1582
	s_waitcnt lgkmcnt(0)
	v_add_f32_e32 v36, v34, v35
	v_lshlrev_b64 v[34:35], 6, v[58:59]
	s_lshl_b32 s12, s20, 2
	v_lshl_add_u64 v[34:35], s[28:29], 0, v[34:35]
	s_ashr_i32 s13, s12, 31
	v_lshl_add_u64 v[34:35], s[12:13], 2, v[34:35]
	s_lshl_b32 s56, s78, 2
	v_lshl_add_u64 v[34:35], v[34:35], 0, s[56:57]
	global_store_dword v[34:35], v36, off sc1
	s_nop 1
; __device__ __forceinline__ void st16_wt(void* p, u32x4 v) { asm volatile("global_store_dwordx4 %0, %1, off sc1\n\ts_nop 1" :: "v"(p), "v"(v) : "memory"); }
; __device__ __forceinline__ void st16_wt(void* p, f32x4 v) { asm volatile("global_store_dwordx4 %0, %1, off sc1\n\ts_nop 1" :: "v"(p), "v"(v) : "memory"); }
; __device__ __forceinline__ void st4_wt(float* p, float v) { asm volatile("global_store_dword %0, %1, off sc1\n\ts_nop 1" :: "v"(p), "v"(v) : "memory"); }
; __device__ __forceinline__ u32x4 pack8(const f32x4& a, const f32x4& b) { u32x4 w; w.x = cvt_pk_bf16(a[0], a[1]); w.y = cvt_pk_bf16(a[2], a[3]); w.z = cvt_pk_bf16(b[0], b[1]); w.w = cvt_pk_bf16(b[2], b[3]); return w; }
; __device__ __forceinline__ float hsq4(const f32x4& v) { return (v[0] * v[0] + v[1] * v[1]) + (v[2] * v[2] + v[3] * v[3]); }
; __device__ __forceinline__ float red_fq(float s) { s += shfl_xor_(s, 16); s += shfl_xor_(s, 32); return s; }
; __device__ __forceinline__ f32x4 unpk_lo(unsigned a, unsigned b) { return (f32x4){__uint_as_float(a << 16), __uint_as_float(a & 0xffff0000u), __uint_as_float(b << 16), __uint_as_float(b & 0xffff0000u)}; }
;     __device__ __forceinline__ void operator()(const f32x4 (&acc)[2][2][4][2], const Unit& u, int wr, int wc, int fr, int fq) const {
;     ...
;             for (int m = 0; m < 4; ++m) { const int row = u.pm * BM + ai * HALF + wr * 64 + m * 16 + fr;
;                 float s = 0.f;
; #pragma unroll
;                 for (int bj = 0; bj < 2; ++bj) { const size_t o = (size_t)row * DM + u.pn * 256 + bj * HALF + cb;
;                     f32x4 a0, a1;
;                     if (xin_f32) { a0 = *(const f32x4*)(xin_f32 + o); a1 = *(const f32x4*)(xin_f32 + o + 4); }
;                     else { const u32x4 w = rw[m][bj]; a0 = unpk_lo(w.x, w.y); a1 = unpk_lo(w.z, w.w); }
;                     a0 = a0 + acc[ai][bj][m][0]; a1 = a1 + acc[ai][bj][m][1];
;                     if (WT) st16_wt(xb + o, pack8(a0, a1)); else *(u32x4*)(xb + o) = pack8(a0, a1); s += hsq4(a0) + hsq4(a1); }
;                 s = red_fq(s); if (fq == 0) { if (WT) st4_wt(rsx + (size_t)row * 16 + u.pn * 4 + wc, s); else rsx[(size_t)row * 16 + u.pn * 4 + wc] = s; }
;                 asm volatile("" ::: "memory"); } }
.LBB0_1582:
	s_or_b64 exec, exec, s[58:59]
	v_add_u32_e32 v42, 0xa0, v180
	v_ashrrev_i32_e32 v43, 31, v42
	s_waitcnt lgkmcnt(0)
	v_lshlrev_b64 v[34:35], 10, v[42:43]
	v_lshl_add_u64 v[34:35], v[34:35], 0, v[182:183]
	v_lshl_add_u64 v[48:49], v[34:35], 0, s[54:55]
	s_and_b64 vcc, exec, s[6:7]
	v_lshl_add_u64 v[44:45], v[48:49], 2, s[24:25]
	s_cbranch_vccnz .LBB0_1619
	global_load_dwordx4 v[38:41], v[44:45], off offset:16
	global_load_dwordx4 v[34:37], v[44:45], off
	s_waitcnt vmcnt(0)
	s_cbranch_execnz .LBB0_1585
.LBB0_1584:
	v_lshlrev_b32_e32 v34, 16, v90
	v_and_b32_e32 v35, 0xffff0000, v90
	v_lshlrev_b32_e32 v36, 16, v91
	v_and_b32_e32 v37, 0xffff0000, v91
	v_lshlrev_b32_e32 v38, 16, v92
	v_and_b32_e32 v39, 0xffff0000, v92
	v_lshlrev_b32_e32 v40, 16, v93
	v_and_b32_e32 v41, 0xffff0000, v93
.LBB0_1585:
	v_pk_add_f32 v[36:37], v[32:33], v[36:37]
	v_pk_add_f32 v[46:47], v[30:31], v[34:35]
	v_pk_add_f32 v[40:41], v[28:29], v[40:41]
	v_pk_add_f32 v[38:39], v[26:27], v[38:39]
	v_lshl_add_u64 v[34:35], v[48:49], 1, s[26:27]
	v_cvt_pk_bf16_f32 v26, v46, v47
	v_cvt_pk_bf16_f32 v27, v36, v37
	v_cvt_pk_bf16_f32 v28, v38, v39
	v_cvt_pk_bf16_f32 v29, v40, v41
	s_and_b64 vcc, exec, s[6:7]
	global_store_dwordx4 v[34:35], v[26:29], off sc1
	s_nop 1
	s_cbranch_vccnz .LBB0_1620
	global_load_dwordx4 v[30:33], v[44:45], off offset:528
	global_load_dwordx4 v[26:29], v[44:45], off offset:512
	s_waitcnt vmcnt(0)
	s_cbranch_execnz .LBB0_1588
.LBB0_1587:
	v_lshlrev_b32_e32 v26, 16, v82
	v_and_b32_e32 v27, 0xffff0000, v82
	v_lshlrev_b32_e32 v28, 16, v83
	v_and_b32_e32 v29, 0xffff0000, v83
	v_lshlrev_b32_e32 v30, 16, v84
	v_and_b32_e32 v31, 0xffff0000, v84
	v_lshlrev_b32_e32 v32, 16, v85
	v_and_b32_e32 v33, 0xffff0000, v85
.LBB0_1588:
	v_pk_add_f32 v[24:25], v[24:25], v[28:29]
	v_pk_add_f32 v[22:23], v[22:23], v[26:27]
	v_pk_add_f32 v[28:29], v[18:19], v[30:31]
	s_mov_b64 s[12:13], 0x100
	v_cvt_pk_bf16_f32 v18, v22, v23
	v_cvt_pk_bf16_f32 v19, v24, v25
	v_mul_f32_e32 v44, v47, v47
	v_mul_f32_e32 v37, v37, v37
	v_pk_add_f32 v[26:27], v[20:21], v[32:33]
	v_lshl_add_u64 v[30:31], v[34:35], 0, s[12:13]
	v_cvt_pk_bf16_f32 v20, v28, v29
	v_cvt_pk_bf16_f32 v21, v26, v27
	v_fmac_f32_e32 v44, v46, v46
	global_store_dwordx4 v[30:31], v[18:21], off sc1
	s_nop 1
	v_mul_f32_e32 v18, v23, v23
	v_mul_f32_e32 v19, v25, v25
	v_fmac_f32_e32 v37, v36, v36
	v_fmac_f32_e32 v18, v22, v22
	v_fmac_f32_e32 v19, v24, v24
	v_add_f32_e32 v36, v44, v37
	v_mul_f32_e32 v37, v39, v39
	v_add_f32_e32 v18, v18, v19
	v_mul_f32_e32 v19, v29, v29
	v_mul_f32_e32 v20, v27, v27
	v_fmac_f32_e32 v37, v38, v38
	v_mul_f32_e32 v38, v41, v41
	v_fmac_f32_e32 v19, v28, v28
	v_fmac_f32_e32 v20, v26, v26
	v_fmac_f32_e32 v38, v40, v40
	v_add_f32_e32 v19, v19, v20
	v_add_f32_e32 v37, v37, v38
	v_add_f32_e32 v18, v18, v19
	v_mbcnt_lo_u32_b32 v19, -1, 0
	v_mbcnt_hi_u32_b32 v19, -1, v19
	v_add_f32_e32 v36, v36, v37
	v_lshlrev_b32_e32 v19, 2, v19
	v_add_f32_e32 v18, v36, v18
	v_xor_b32_e32 v19, 64, v19
	ds_bpermute_b32 v19, v19, v18
	s_waitcnt lgkmcnt(0)
	v_add_f32_e32 v18, v18, v19
	v_mbcnt_lo_u32_b32 v19, -1, 0
	v_mbcnt_hi_u32_b32 v19, -1, v19
	s_nop 0
	v_lshlrev_b32_e32 v19, 2, v19
	v_xor_b32_e32 v19, 0x80, v19
	ds_bpermute_b32 v19, v19, v18
	s_and_saveexec_b64 s[58:59], s[8:9]
	s_cbranch_execz .LBB0_1590
	s_waitcnt lgkmcnt(0)
	v_add_f32_e32 v20, v18, v19
	v_lshlrev_b64 v[18:19], 6, v[42:43]
	s_lshl_b32 s12, s20, 2
	v_lshl_add_u64 v[18:19], s[28:29], 0, v[18:19]
	s_ashr_i32 s13, s12, 31
	v_lshl_add_u64 v[18:19], s[12:13], 2, v[18:19]
	s_lshl_b32 s56, s78, 2
	v_lshl_add_u64 v[18:19], v[18:19], 0, s[56:57]
	global_store_dword v[18:19], v20, off sc1
	s_nop 1
; __device__ __forceinline__ void st16_wt(void* p, u32x4 v) { asm volatile("global_store_dwordx4 %0, %1, off sc1\n\ts_nop 1" :: "v"(p), "v"(v) : "memory"); }
; __device__ __forceinline__ void st16_wt(void* p, f32x4 v) { asm volatile("global_store_dwordx4 %0, %1, off sc1\n\ts_nop 1" :: "v"(p), "v"(v) : "memory"); }
; __device__ __forceinline__ void st4_wt(float* p, float v) { asm volatile("global_store_dword %0, %1, off sc1\n\ts_nop 1" :: "v"(p), "v"(v) : "memory"); }
; __device__ __forceinline__ u32x4 pack8(const f32x4& a, const f32x4& b) { u32x4 w; w.x = cvt_pk_bf16(a[0], a[1]); w.y = cvt_pk_bf16(a[2], a[3]); w.z = cvt_pk_bf16(b[0], b[1]); w.w = cvt_pk_bf16(b[2], b[3]); return w; }
; __device__ __forceinline__ float hsq4(const f32x4& v) { return (v[0] * v[0] + v[1] * v[1]) + (v[2] * v[2] + v[3] * v[3]); }
; __device__ __forceinline__ float red_fq(float s) { s += shfl_xor_(s, 16); s += shfl_xor_(s, 32); return s; }
; __device__ __forceinline__ f32x4 unpk_lo(unsigned a, unsigned b) { return (f32x4){__uint_as_float(a << 16), __uint_as_float(a & 0xffff0000u), __uint_as_float(b << 16), __uint_as_float(b & 0xffff0000u)}; }
;     __device__ __forceinline__ void operator()(const f32x4 (&acc)[2][2][4][2], const Unit& u, int wr, int wc, int fr, int fq) const {
;     ...
;             for (int m = 0; m < 4; ++m) { const int row = u.pm * BM + ai * HALF + wr * 64 + m * 16 + fr;
;                 float s = 0.f;
; #pragma unroll
;                 for (int bj = 0; bj < 2; ++bj) { const size_t o = (size_t)row * DM + u.pn * 256 + bj * HALF + cb;
;                     f32x4 a0, a1;
;                     if (xin_f32) { a0 = *(const f32x4*)(xin_f32 + o); a1 = *(const f32x4*)(xin_f32 + o + 4); }
;                     else { const u32x4 w = rw[m][bj]; a0 = unpk_lo(w.x, w.y); a1 = unpk_lo(w.z, w.w); }
;                     a0 = a0 + acc[ai][bj][m][0]; a1 = a1 + acc[ai][bj][m][1];
;                     if (WT) st16_wt(xb + o, pack8(a0, a1)); else *(u32x4*)(xb + o) = pack8(a0, a1); s += hsq4(a0) + hsq4(a1); }
;                 s = red_fq(s); if (fq == 0) { if (WT) st4_wt(rsx + (size_t)row * 16 + u.pn * 4 + wc, s); else rsx[(size_t)row * 16 + u.pn * 4 + wc] = s; }
;                 asm volatile("" ::: "memory"); } }
.LBB0_1590:
	s_or_b64 exec, exec, s[58:59]
	v_add_u32_e32 v26, 0xb0, v180
	v_ashrrev_i32_e32 v27, 31, v26
	s_waitcnt lgkmcnt(0)
	v_lshlrev_b64 v[18:19], 10, v[26:27]
	v_lshl_add_u64 v[18:19], v[18:19], 0, v[182:183]
	v_lshl_add_u64 v[32:33], v[18:19], 0, s[54:55]
	s_and_b64 vcc, exec, s[6:7]
	v_lshl_add_u64 v[28:29], v[32:33], 2, s[24:25]
	s_cbranch_vccnz .LBB0_1621
	global_load_dwordx4 v[22:25], v[28:29], off offset:16
	global_load_dwordx4 v[18:21], v[28:29], off
	s_waitcnt vmcnt(0)
	s_cbranch_execnz .LBB0_1593
.LBB0_1592:
	v_lshlrev_b32_e32 v18, 16, v70
	v_and_b32_e32 v19, 0xffff0000, v70
	v_lshlrev_b32_e32 v20, 16, v71
	v_and_b32_e32 v21, 0xffff0000, v71
	v_lshlrev_b32_e32 v22, 16, v72
	v_and_b32_e32 v23, 0xffff0000, v72
	v_lshlrev_b32_e32 v24, 16, v73
	v_and_b32_e32 v25, 0xffff0000, v73
.LBB0_1593:
	v_pk_add_f32 v[20:21], v[16:17], v[20:21]
	v_pk_add_f32 v[30:31], v[14:15], v[18:19]
	v_pk_add_f32 v[24:25], v[12:13], v[24:25]
	v_pk_add_f32 v[22:23], v[10:11], v[22:23]
	v_lshl_add_u64 v[18:19], v[32:33], 1, s[26:27]
	v_cvt_pk_bf16_f32 v10, v30, v31
	v_cvt_pk_bf16_f32 v11, v20, v21
	v_cvt_pk_bf16_f32 v12, v22, v23
	v_cvt_pk_bf16_f32 v13, v24, v25
	s_and_b64 vcc, exec, s[6:7]
	global_store_dwordx4 v[18:19], v[10:13], off sc1
	s_nop 1
	s_cbranch_vccnz .LBB0_1622
	global_load_dwordx4 v[14:17], v[28:29], off offset:528
	global_load_dwordx4 v[10:13], v[28:29], off offset:512
	s_waitcnt vmcnt(0)
	s_cbranch_execnz .LBB0_1596
.LBB0_1595:
	v_lshlrev_b32_e32 v10, 16, v66
	v_and_b32_e32 v11, 0xffff0000, v66
	v_lshlrev_b32_e32 v12, 16, v67
	v_and_b32_e32 v13, 0xffff0000, v67
	v_lshlrev_b32_e32 v14, 16, v68
	v_and_b32_e32 v15, 0xffff0000, v68
	v_lshlrev_b32_e32 v16, 16, v69
	v_and_b32_e32 v17, 0xffff0000, v69
.LBB0_1596:
	v_pk_add_f32 v[8:9], v[8:9], v[12:13]
	v_pk_add_f32 v[6:7], v[6:7], v[10:11]
	v_pk_add_f32 v[12:13], v[2:3], v[14:15]
	s_mov_b64 s[6:7], 0x100
	v_cvt_pk_bf16_f32 v2, v6, v7
	v_cvt_pk_bf16_f32 v3, v8, v9
	v_mul_f32_e32 v28, v31, v31
	v_mul_f32_e32 v21, v21, v21
	v_pk_add_f32 v[10:11], v[4:5], v[16:17]
	v_lshl_add_u64 v[14:15], v[18:19], 0, s[6:7]
	v_cvt_pk_bf16_f32 v4, v12, v13
	v_cvt_pk_bf16_f32 v5, v10, v11
	v_fmac_f32_e32 v28, v30, v30
	global_store_dwordx4 v[14:15], v[2:5], off sc1
	s_nop 1
	v_mul_f32_e32 v2, v7, v7
	v_mul_f32_e32 v3, v9, v9
	v_fmac_f32_e32 v21, v20, v20
	v_fmac_f32_e32 v2, v6, v6
	v_fmac_f32_e32 v3, v8, v8
	v_add_f32_e32 v20, v28, v21
	v_mul_f32_e32 v21, v23, v23
	v_add_f32_e32 v2, v2, v3
	v_mul_f32_e32 v3, v13, v13
	v_mul_f32_e32 v4, v11, v11
	v_fmac_f32_e32 v21, v22, v22
	v_mul_f32_e32 v22, v25, v25
	v_fmac_f32_e32 v3, v12, v12
	v_fmac_f32_e32 v4, v10, v10
	v_fmac_f32_e32 v22, v24, v24
	v_add_f32_e32 v3, v3, v4
	v_add_f32_e32 v21, v21, v22
	v_add_f32_e32 v2, v2, v3
	v_mbcnt_lo_u32_b32 v3, -1, 0
	v_mbcnt_hi_u32_b32 v3, -1, v3
	v_add_f32_e32 v20, v20, v21
	v_lshlrev_b32_e32 v3, 2, v3
	v_add_f32_e32 v2, v20, v2
	v_xor_b32_e32 v3, 64, v3
	ds_bpermute_b32 v3, v3, v2
	s_waitcnt lgkmcnt(0)
	v_add_f32_e32 v2, v2, v3
	v_mbcnt_lo_u32_b32 v3, -1, 0
	v_mbcnt_hi_u32_b32 v3, -1, v3
	s_nop 0
	v_lshlrev_b32_e32 v3, 2, v3
	v_xor_b32_e32 v3, 0x80, v3
	ds_bpermute_b32 v3, v3, v2
	s_and_saveexec_b64 s[6:7], s[8:9]
	s_cbranch_execz .LBB0_1598
	s_waitcnt lgkmcnt(0)
	v_add_f32_e32 v4, v2, v3
	v_lshlrev_b64 v[2:3], 6, v[26:27]
	s_lshl_b32 s8, s20, 2
	v_lshl_add_u64 v[2:3], s[28:29], 0, v[2:3]
	s_ashr_i32 s9, s8, 31
	v_lshl_add_u64 v[2:3], s[8:9], 2, v[2:3]
	s_lshl_b32 s56, s78, 2
	v_lshl_add_u64 v[2:3], v[2:3], 0, s[56:57]
	global_store_dword v[2:3], v4, off sc1
	s_nop 1
